# attention: removed the 16 P-repacking permlane32 swaps per 2 tiles; V tr-read addressing (half/second-read terms swapped) delivers keys in the QK accumulator order
# speedup vs baseline: 1.0108x; 1.0108x over previous
; DI int v_st(int k, int c) { const int kk = (k & ~0xC) | ((k & 4) << 1) | ((k & 8) >> 1); return ((kk >> 3) * 4 + (c >> 5)) * 512 + ((kk & 7) * 32 + (c & 31)) * 2; }
; DI int v_rd_base(int lane) { return ((lane & 3) << 3) | (((lane >> 2) & 3) << 6) | (((lane >> 4) & 1) << 5) | (((lane >> 5) & 1) << 8); }
; #define SLOADA(k0) do { vsA0 = *reinterpret_cast<const bf16x8*>(&Vh[(size_t)((k0) + sr) * LDQ + sc]); vsA1 = *reinterpret_cast<const bf16x8*>(&Vh[(size_t)((k0) + 32 + sr) * LDQ + sc]); \
;     ksA = *reinterpret_cast<const bf16x8*>(&Kh[(size_t)((k0) + kr) * LDQ + kc]); } while (0)
; #define SLOADB(k0) do { vsB0 = *reinterpret_cast<const bf16x8*>(&Vh[(size_t)((k0) + sr) * LDQ + sc]); vsB1 = *reinterpret_cast<const bf16x8*>(&Vh[(size_t)((k0) + 32 + sr) * LDQ + sc]); \
;     ksB = *reinterpret_cast<const bf16x8*>(&Kh[(size_t)((k0) + kr) * LDQ + kc]); } while (0)
; #define SWRITEA(b) do { *(bf16x8*)(V_lds + (b) * SHM_V + vst0) = vsA0; *(bf16x8*)(V_lds + (b) * SHM_V + vst1) = vsA1; *(bf16x8*)(K_lds + (b) * SHM_K + kst) = ksA; } while (0)
; #define SWRITEB(b) do { *(bf16x8*)(V_lds + (b) * SHM_V + vst0) = vsB0; *(bf16x8*)(V_lds + (b) * SHM_V + vst1) = vsB1; *(bf16x8*)(K_lds + (b) * SHM_K + kst) = ksB; } while (0)
; #define SWAIT() asm volatile("s_waitcnt vmcnt(3)" ::: "memory")
; DI void attn_pass(const bf16_t* __restrict__ Qb, const bf16_t* __restrict__ Kh, const bf16_t* __restrict__ Vh, int seq, char* lds, f32x16 (&o)[4], float& l_out) {
;     ...
;     const int sr = tid >> 4, sc = (tid & 15) * 8, vst0 = v_st(sr, sc), vst1 = v_st(32 + sr, sc);
;     const int kr = tid >> 3, kc = (tid & 7) * 8, kst = KSWZ(kr, kc * 2);
;     const int vb0 = (int)(uintptr_t)V_lds + v_rd_base(lane);
;     bf16x8 vsA0, vsA1, ksA, vsB0, vsB1, ksB;
;     ...
;     f32x16 pA0, pA1, pB0, pB1; float alA, alB; bf16x8 pa0, pa1, pa2, pa3; const int NT = seq / KVBLK;
;     SLOADA(0); asm volatile("s_waitcnt vmcnt(0)" ::: "memory"); SWRITEA(0); __syncthreads();
;     qkt(pA0, pA1, K_lds, qr, negm, r32, hi); partialSM(pA0, pA1, m_reg, negm, alA);
;     SLOADB(KVBLK); if (2 < NT) SLOADA(2 * KVBLK);
;     SWAIT(); SWRITEB(1); __syncthreads();
;     for (int j = 1; j + 1 < NT; j += 2) {
.LBB0_1037:
	v_mov_b32_e32 v25, v185
	v_lshl_add_u64 v[38:39], v[22:23], 0, v[24:25]
	s_mov_b32 s16, 0x20000
	v_add_co_u32_e32 v22, vcc, s16, v38
	s_mov_b32 s2, 0x30000
	s_nop 0
	v_addc_co_u32_e32 v23, vcc, 0, v39, vcc
	v_add_co_u32_e32 v30, vcc, s2, v38
	v_mov_b32_e32 v21, v185
	s_nop 0
	v_addc_co_u32_e32 v31, vcc, 0, v39, vcc
	v_lshl_add_u64 v[20:21], v[26:27], 0, v[20:21]
	v_add_co_u32_e32 v26, vcc, s16, v20
	v_exp_f32_e32 v207, v0
	s_nop 0
	v_addc_co_u32_e32 v27, vcc, 0, v21, vcc
	v_add_co_u32_e32 v0, vcc, s3, v20
	s_xor_b64 s[16:17], s[6:7], -1
	v_exp_f32_e32 v209, v1
	v_addc_co_u32_e32 v1, vcc, 0, v21, vcc
	s_mov_b32 s6, 0x50000
	v_exp_f32_e32 v183, v2
	v_add_co_u32_e32 v2, vcc, s6, v38
	v_exp_f32_e32 v208, v3
	s_nop 0
	v_addc_co_u32_e32 v3, vcc, 0, v39, vcc
	global_load_dwordx4 v[22:25], v[22:23], off
	s_nop 0
	global_load_dwordx4 v[30:33], v[30:31], off
	v_exp_f32_e32 v181, v4
	v_add_co_u32_e32 v4, vcc, s3, v38
	global_load_dwordx4 v[34:37], v[26:27], off
	v_exp_f32_e32 v206, v5
	v_addc_co_u32_e32 v5, vcc, 0, v39, vcc
	global_load_dwordx4 v[168:171], v[0:1], off
	global_load_dwordx4 v[164:167], v[2:3], off
	global_load_dwordx4 v[160:163], v[4:5], off
	s_cmp_lg_u32 0, -1
	s_cselect_b32 s25, 0, 0
	s_add_i32 s26, s25, 0x4000
	s_add_u32 s18, s18, s23
	v_and_b32_e32 v0, 7, v28
	s_addc_u32 s19, s19, 0
	v_and_b32_e32 v26, 63, v28
	v_mov_b32_e32 v1, v185
	v_lshlrev_b32_e32 v0, 4, v0
	s_add_u32 s4, s18, s4
	v_lshlrev_b32_e32 v3, 4, v26
	v_lshl_add_u64 v[0:1], v[18:19], 0, v[0:1]
	s_addc_u32 s5, s19, s5
	v_lshlrev_b32_e32 v2, 3, v26
	v_lshlrev_b32_e32 v4, 1, v26
	v_and_b32_e32 v3, 0xc0, v3
	v_mov_b32_e32 v202, v0
	s_add_u32 s100, s4, s14
	s_addc_u32 s101, s5, s15
	s_add_u32 s100, s100, 0x13c60000
	s_addc_u32 s101, s101, 0
	v_and_b32_e32 v0, 15, v28
	v_and_b32_e32 v27, 0x3fffffc0, v28
	v_exp_f32_e32 v180, v6
	v_exp_f32_e32 v182, v7
	v_exp_f32_e32 v173, v8
	v_exp_f32_e32 v175, v9
	v_exp_f32_e32 v172, v10
	v_exp_f32_e32 v174, v11
	v_exp_f32_e32 v177, v12
	v_exp_f32_e32 v179, v13
	v_exp_f32_e32 v176, v14
	v_exp_f32_e32 v178, v15
	v_and_b32_e32 v4, 32, v4
	v_lshlrev_b32_e32 v5, 6, v26
	v_and_b32_e32 v5, 0x800, v5
	v_and_or_b32 v2, v2, 24, v3
	s_add_u32 s4, s8, s23
	v_lshlrev_b32_e32 v0, 4, v0
	v_mov_b32_e32 v1, v185
	v_lshl_add_u32 v211, v27, 2, 0
	s_waitcnt vmcnt(3)
	v_or3_b32 v2, v2, v4, v5
	s_addc_u32 s5, s9, 0
	v_lshl_add_u64 v[0:1], v[16:17], 0, v[0:1]
	v_mov_b32_e32 v14, v185
	v_mov_b32_e32 v15, v185
	v_cmp_gt_u32_e64 s[6:7], 32, v26
	v_lshl_add_u32 v212, v29, 2, v211
	v_add_u32_e32 v220, s25, v2
	v_add_u32_e32 v201, s26, v2
	s_waitcnt vmcnt(5)
	ds_write_b128 v214, v[22:25] offset:16384
	s_waitcnt vmcnt(4)
	ds_write_b128 v215, v[30:33] offset:16384
	s_waitcnt vmcnt(3)
	ds_write_b128 v213, v[34:37] offset:40960
	v_mov_b32_e32 v203, v0
	v_add_u32_e32 v204, 0x10000, v0
	s_add_u32 s98, s4, s14
	s_addc_u32 s99, s5, s15
	s_add_u32 s98, s98, 0x19c60000
	s_addc_u32 s99, s99, 0
	v_mov_b32_e32 v0, v185
	v_mov_b32_e32 v1, v185
	v_mov_b32_e32 v2, v185
	v_mov_b32_e32 v3, v185
	v_mov_b32_e32 v4, v185
	v_mov_b32_e32 v5, v185
	v_mov_b32_e32 v6, v185
	v_mov_b32_e32 v7, v185
	v_mov_b32_e32 v8, v185
	v_mov_b32_e32 v9, v185
	v_mov_b32_e32 v10, v185
	v_mov_b32_e32 v11, v185
	v_mov_b32_e32 v12, v185
	v_mov_b32_e32 v13, v185
	v_mov_b64_e32 v[30:31], v[14:15]
	v_mov_b64_e32 v[46:47], v[14:15]
	v_mov_b64_e32 v[62:63], v[14:15]
	s_mov_b32 s2, 4
	v_mov_b32_e32 v210, 0
	v_mov_b32_e32 v221, s24
	v_mov_b64_e32 v[28:29], v[12:13]
	v_mov_b64_e32 v[26:27], v[10:11]
	v_mov_b64_e32 v[24:25], v[8:9]
	v_mov_b64_e32 v[22:23], v[6:7]
	v_mov_b64_e32 v[20:21], v[4:5]
	v_mov_b64_e32 v[18:19], v[2:3]
	v_mov_b64_e32 v[16:17], v[0:1]
	v_mov_b64_e32 v[44:45], v[12:13]
	v_mov_b64_e32 v[42:43], v[10:11]
	v_mov_b64_e32 v[40:41], v[8:9]
	v_mov_b64_e32 v[38:39], v[6:7]
	v_mov_b64_e32 v[36:37], v[4:5]
	v_mov_b64_e32 v[34:35], v[2:3]
	v_mov_b64_e32 v[32:33], v[0:1]
	v_mov_b64_e32 v[60:61], v[12:13]
	v_mov_b64_e32 v[58:59], v[10:11]
	v_mov_b64_e32 v[56:57], v[8:9]
	v_mov_b64_e32 v[54:55], v[6:7]
	v_mov_b64_e32 v[52:53], v[4:5]
	v_mov_b64_e32 v[50:51], v[2:3]
	v_mov_b64_e32 v[48:49], v[0:1]
	v_mov_b32_e32 v65, v64
	v_mov_b32_e32 v66, v64
	v_mov_b32_e32 v67, v64
	v_mov_b32_e32 v68, v64
	v_mov_b32_e32 v69, v64
	v_mov_b32_e32 v70, v64
	v_mov_b32_e32 v71, v64
	v_mov_b32_e32 v72, v64
	v_mov_b32_e32 v73, v64
	v_mov_b32_e32 v74, v64
	v_mov_b32_e32 v75, v64
	v_mov_b32_e32 v76, v64
	v_mov_b32_e32 v77, v64
	v_mov_b32_e32 v78, v64
	v_mov_b32_e32 v79, v64
	s_waitcnt lgkmcnt(0)
	s_barrier
; DI void finishSM(f32x16& p0, f32x16& p1, float alpha, float& l_reg, bf16x8& pa0, bf16x8& pa1, bf16x8& pa2, bf16x8& pa3) {
; #pragma unroll
;     for (int r = 0; r < 16; ++r) p1[r] = __builtin_amdgcn_exp2f(p1[r]);
;     float ps = 0;
; #pragma unroll
;     for (int r = 0; r < 16; ++r) ps += p0[r];
; #pragma unroll
;     for (int r = 0; r < 16; ++r) ps += p1[r];
;     { auto rr = __builtin_amdgcn_permlane32_swap(__float_as_uint(ps), __float_as_uint(ps), false, false);
;       ps = __uint_as_float(rr[0]) + __uint_as_float(rr[1]); }
;     l_reg = l_reg * alpha + ps;
;     ...
;     PK4(p0, 0, pa0); PK4(p0, 8, pa1); PK4(p1, 0, pa2); PK4(p1, 8, pa3);
;     ...
; }
; DI void qkt(f32x16& p0, f32x16& p1, const char* Ks, const bf16x8* qr, const f32x16& negm, int r32, int hi) {
;     { const bf16x8 b0 = *reinterpret_cast<const bf16x8*>(Ks + KSWZ(r32, hi * 16));
;       const bf16x8 b1 = *reinterpret_cast<const bf16x8*>(Ks + KSWZ(32 + r32, hi * 16));
;       p0 = __builtin_amdgcn_mfma_f32_32x32x16_bf16(b0, qr[0], negm, 0, 0, 0);
;       p1 = __builtin_amdgcn_mfma_f32_32x32x16_bf16(b1, qr[0], negm, 0, 0, 0); }
; #pragma unroll
;     for (int d0 = 1; d0 < 4; ++d0) { const int cb = (d0 * 16 + hi * 8) * 2;
;         const bf16x8 b0 = *reinterpret_cast<const bf16x8*>(Ks + KSWZ(r32, cb));
;         const bf16x8 b1 = *reinterpret_cast<const bf16x8*>(Ks + KSWZ(32 + r32, cb));
;         p0 = __builtin_amdgcn_mfma_f32_32x32x16_bf16(b0, qr[d0], p0, 0, 0, 0);
;         p1 = __builtin_amdgcn_mfma_f32_32x32x16_bf16(b1, qr[d0], p1, 0, 0, 0); }
; }
; DI int v_st(int k, int c) { const int kk = (k & ~0xC) | ((k & 4) << 1) | ((k & 8) >> 1); return ((kk >> 3) * 4 + (c >> 5)) * 512 + ((kk & 7) * 32 + (c & 31)) * 2; }
; DI int v_rd_base(int lane) { return ((lane & 3) << 3) | (((lane >> 2) & 3) << 6) | (((lane >> 4) & 1) << 5) | (((lane >> 5) & 1) << 8); }
; template <int OFF> DI s16x4 tr_read(int vb) { s16x4 r; asm volatile("ds_read_b64_tr_b16 %0, %1 offset:%2" : "=&v"(r) : "v"(vb), "i"(OFF) : "memory"); return r; }
; template <int D0> DI void pv_one(f32x16& od, int vb, bf16x8 pa0, bf16x8 pa1, bf16x8 pa2, bf16x8 pa3) {
;     const s16x4 l0 = tr_read<v_rd_off(D0, 0, 0)>(vb), h0 = tr_read<v_rd_off(D0, 0, 1)>(vb), l1 = tr_read<v_rd_off(D0, 1, 0)>(vb), h1 = tr_read<v_rd_off(D0, 1, 1)>(vb);
.LBB0_1038:
	ds_read_b128 v[80:83], v217 offset:40960
	ds_read_b128 v[84:87], v217 offset:45056
	v_exp_f32_e32 v88, v96
	v_exp_f32_e32 v89, v97
	v_exp_f32_e32 v90, v98
	s_waitcnt lgkmcnt(1)
	v_mfma_f32_32x32x16_bf16 v[128:143], v[80:83], v[148:151], v[64:79]
	v_exp_f32_e32 v91, v99
	v_exp_f32_e32 v92, v100
	v_exp_f32_e32 v93, v101
	v_exp_f32_e32 v94, v102
	v_exp_f32_e32 v95, v103
	v_exp_f32_e32 v96, v104
	v_exp_f32_e32 v97, v105
	s_waitcnt lgkmcnt(0)
	v_mfma_f32_32x32x16_bf16 v[112:127], v[84:87], v[148:151], v[64:79]
	ds_read_b128 v[80:83], v218 offset:40960
	ds_read_b128 v[84:87], v218 offset:45056
	v_exp_f32_e32 v98, v106
	v_exp_f32_e32 v99, v107
	v_exp_f32_e32 v100, v108
	v_exp_f32_e32 v101, v109
	v_exp_f32_e32 v102, v110
	v_exp_f32_e32 v103, v111
	s_waitcnt lgkmcnt(1)
	v_mfma_f32_32x32x16_bf16 v[128:143], v[80:83], v[144:147], v[128:143]
	s_waitcnt lgkmcnt(0)
	v_mfma_f32_32x32x16_bf16 v[112:127], v[84:87], v[144:147], v[112:127]
	ds_read_b128 v[80:83], v219 offset:40960
	ds_read_b128 v[84:87], v219 offset:45056
	s_waitcnt lgkmcnt(1)
	v_mfma_f32_32x32x16_bf16 v[128:143], v[80:83], v[152:155], v[128:143]
	s_waitcnt lgkmcnt(0)
	v_mfma_f32_32x32x16_bf16 v[112:127], v[84:87], v[152:155], v[112:127]
	ds_read_b128 v[80:83], v216 offset:40960
	ds_read_b128 v[84:87], v216 offset:45056
	s_waitcnt lgkmcnt(1)
	v_mfma_f32_32x32x16_bf16 v[128:143], v[80:83], v[156:159], v[128:143]
	v_add_f32_e32 v80, v209, v207
	v_add_f32_e32 v80, v183, v80
	v_add_f32_e32 v80, v208, v80
	v_add_f32_e32 v80, v181, v80
	v_add_f32_e32 v80, v206, v80
	v_add_f32_e32 v80, v180, v80
	v_add_f32_e32 v80, v182, v80
	v_add_f32_e32 v80, v173, v80
	v_add_f32_e32 v80, v175, v80
	v_add_f32_e32 v80, v172, v80
	v_add_f32_e32 v80, v174, v80
	v_add_f32_e32 v80, v177, v80
	v_add_f32_e32 v80, v179, v80
	v_add_f32_e32 v80, v176, v80
	v_add_f32_e32 v80, v178, v80
	v_add_f32_e32 v80, v88, v80
	v_add_f32_e32 v80, v89, v80
	v_add_f32_e32 v80, v90, v80
	v_add_f32_e32 v80, v91, v80
	v_add_f32_e32 v80, v92, v80
	v_add_f32_e32 v80, v93, v80
	v_add_f32_e32 v80, v94, v80
	v_add_f32_e32 v80, v95, v80
	v_add_f32_e32 v80, v96, v80
	v_add_f32_e32 v80, v97, v80
	s_waitcnt lgkmcnt(0)
	v_mfma_f32_32x32x16_bf16 v[112:127], v[84:87], v[156:159], v[112:127]
	v_add_f32_e32 v80, v98, v80
	v_add_f32_e32 v80, v99, v80
	v_add_f32_e32 v80, v100, v80
	v_add_f32_e32 v80, v101, v80
	v_add_f32_e32 v80, v102, v80
	v_add_f32_e32 v222, v103, v80
	v_mov_b32_e32 v223, v222
	v_cvt_pk_bf16_f32 v80, v207, v209
	v_cvt_pk_bf16_f32 v81, v183, v208
	v_cvt_pk_bf16_f32 v82, v181, v206
	s_nop 1
	v_permlane32_swap_b32_e32 v222, v223
	v_cvt_pk_bf16_f32 v83, v180, v182
	v_cvt_pk_bf16_f32 v84, v173, v175
	v_cvt_pk_bf16_f32 v85, v172, v174
	v_cvt_pk_bf16_f32 v86, v177, v179
	v_cvt_pk_bf16_f32 v87, v176, v178
	v_cvt_pk_bf16_f32 v88, v88, v89
	v_cvt_pk_bf16_f32 v89, v90, v91
	v_cvt_pk_bf16_f32 v90, v92, v93
	v_cvt_pk_bf16_f32 v91, v94, v95
	v_cvt_pk_bf16_f32 v92, v96, v97
	v_cvt_pk_bf16_f32 v93, v98, v99
	v_cvt_pk_bf16_f32 v94, v100, v101
	v_cvt_pk_bf16_f32 v95, v102, v103
	global_load_dwordx4 v[172:175], v203, s[98:99]
	global_load_dwordx4 v[176:179], v204, s[98:99]
	global_load_dwordx4 v[180:183], v202, s[100:101]
	s_add_u32 s98, s98, 0x20000
	s_addc_u32 s99, s99, 0
	s_add_u32 s100, s100, 0x20000
	s_addc_u32 s101, s101, 0
	ds_read_b64_tr_b16 v[96:97], v220 offset:0
	ds_read_b64_tr_b16 v[98:99], v220 offset:0x100
	ds_read_b64_tr_b16 v[100:101], v220 offset:0x1000
	ds_read_b64_tr_b16 v[102:103], v220 offset:0x1100
	ds_read_b64_tr_b16 v[104:105], v220 offset:0x2000
	ds_read_b64_tr_b16 v[106:107], v220 offset:0x2100
	ds_read_b64_tr_b16 v[108:109], v220 offset:0x3000
	ds_read_b64_tr_b16 v[110:111], v220 offset:0x3100
	s_waitcnt lgkmcnt(0)
	s_nop 0
	v_mfma_f32_32x32x16_bf16 v[48:63], v[80:83], v[96:99], v[48:63]
	ds_read_b64_tr_b16 v[96:97], v220 offset:0x200
	ds_read_b64_tr_b16 v[98:99], v220 offset:0x300
	v_mfma_f32_32x32x16_bf16 v[48:63], v[84:87], v[100:103], v[48:63]
	ds_read_b64_tr_b16 v[100:101], v220 offset:0x1200
	ds_read_b64_tr_b16 v[102:103], v220 offset:0x1300
	v_mfma_f32_32x32x16_bf16 v[48:63], v[88:91], v[104:107], v[48:63]
	ds_read_b64_tr_b16 v[104:105], v220 offset:0x2200
	ds_read_b64_tr_b16 v[106:107], v220 offset:0x2300
	v_mfma_f32_32x32x16_bf16 v[48:63], v[92:95], v[108:111], v[48:63]
	ds_read_b64_tr_b16 v[108:109], v220 offset:0x3200
	ds_read_b64_tr_b16 v[110:111], v220 offset:0x3300
	s_waitcnt lgkmcnt(0)
	v_mfma_f32_32x32x16_bf16 v[32:47], v[80:83], v[96:99], v[32:47]
	ds_read_b64_tr_b16 v[96:97], v220 offset:0x400
	ds_read_b64_tr_b16 v[98:99], v220 offset:0x500
	v_mfma_f32_32x32x16_bf16 v[32:47], v[84:87], v[100:103], v[32:47]
	ds_read_b64_tr_b16 v[100:101], v220 offset:0x1400
	ds_read_b64_tr_b16 v[102:103], v220 offset:0x1500
	v_mfma_f32_32x32x16_bf16 v[32:47], v[88:91], v[104:107], v[32:47]
	ds_read_b64_tr_b16 v[104:105], v220 offset:0x2400
	ds_read_b64_tr_b16 v[106:107], v220 offset:0x2500
	v_mfma_f32_32x32x16_bf16 v[32:47], v[92:95], v[108:111], v[32:47]
	ds_read_b64_tr_b16 v[108:109], v220 offset:0x3400
	ds_read_b64_tr_b16 v[110:111], v220 offset:0x3500
	s_waitcnt lgkmcnt(0)
	v_mfma_f32_32x32x16_bf16 v[16:31], v[80:83], v[96:99], v[16:31]
	ds_read_b64_tr_b16 v[96:97], v220 offset:0x600
	ds_read_b64_tr_b16 v[98:99], v220 offset:0x700
	v_mfma_f32_32x32x16_bf16 v[16:31], v[84:87], v[100:103], v[16:31]
	ds_read_b64_tr_b16 v[100:101], v220 offset:0x1600
	ds_read_b64_tr_b16 v[102:103], v220 offset:0x1700
	v_mfma_f32_32x32x16_bf16 v[16:31], v[88:91], v[104:107], v[16:31]
	ds_read_b64_tr_b16 v[104:105], v220 offset:0x2600
	ds_read_b64_tr_b16 v[106:107], v220 offset:0x2700
	v_mfma_f32_32x32x16_bf16 v[16:31], v[92:95], v[108:111], v[16:31]
	ds_read_b64_tr_b16 v[108:109], v220 offset:0x3600
	ds_read_b64_tr_b16 v[110:111], v220 offset:0x3700
	s_waitcnt lgkmcnt(0)
	v_mfma_f32_32x32x16_bf16 v[0:15], v[80:83], v[96:99], v[0:15]
	v_max_f32_e32 v80, v128, v129
	v_max3_f32 v80, v80, v130, v131
	v_max3_f32 v80, v80, v132, v133
	v_max3_f32 v80, v80, v134, v135
	v_max3_f32 v80, v80, v136, v137
	v_mfma_f32_32x32x16_bf16 v[0:15], v[84:87], v[100:103], v[0:15]
	v_max3_f32 v80, v80, v138, v139
	v_max3_f32 v80, v80, v140, v141
	v_max3_f32 v80, v80, v142, v143
	v_max3_f32 v80, v80, v112, v113
	v_max3_f32 v80, v80, v114, v115
	v_max3_f32 v80, v80, v116, v117
	v_max3_f32 v80, v80, v118, v119
	v_mfma_f32_32x32x16_bf16 v[0:15], v[88:91], v[104:107], v[0:15]
	v_max3_f32 v80, v80, v120, v121
	v_max3_f32 v80, v80, v122, v123
	v_max3_f32 v80, v80, v124, v125
	v_max3_f32 v80, v80, v126, v127
	v_mov_b32_e32 v81, v80
	s_nop 1
	v_permlane32_swap_b32_e32 v80, v81
	v_mfma_f32_32x32x16_bf16 v[0:15], v[92:95], v[108:111], v[0:15]
	v_max_f32_e32 v80, v80, v81
	v_cmp_ngt_f32_e32 vcc, s83, v200
	v_cmp_ge_f32_e64 s[8:9], s63, v80
	s_and_b64 s[4:5], vcc, s[8:9]
	s_cmp_eq_u64 s[4:5], exec
	s_cbranch_scc0 .LBB0_1057
	v_mov_b32_e32 v224, 1.0

; #define SBAR() __builtin_amdgcn_sched_barrier(0)
; #define SLOADA(k0) do { vsA0 = *reinterpret_cast<const bf16x8*>(&Vh[(size_t)((k0) + sr) * LDQ + sc]); vsA1 = *reinterpret_cast<const bf16x8*>(&Vh[(size_t)((k0) + 32 + sr) * LDQ + sc]); \
;     ksA = *reinterpret_cast<const bf16x8*>(&Kh[(size_t)((k0) + kr) * LDQ + kc]); } while (0)
; DI void partialSM(f32x16& p0, f32x16& p1, float& m_reg, f32x16& negm, float& alpha) {
;     ...
;     for (int r = 0; r < 16; ++r) p0[r] = __builtin_amdgcn_exp2f(p0[r]);
; }
; DI void finishSM(f32x16& p0, f32x16& p1, float alpha, float& l_reg, bf16x8& pa0, bf16x8& pa1, bf16x8& pa2, bf16x8& pa3) {
; #pragma unroll
;     for (int r = 0; r < 16; ++r) p1[r] = __builtin_amdgcn_exp2f(p1[r]);
;     float ps = 0;
; #pragma unroll
;     for (int r = 0; r < 16; ++r) ps += p0[r];
; #pragma unroll
;     for (int r = 0; r < 16; ++r) ps += p1[r];
;     { auto rr = __builtin_amdgcn_permlane32_swap(__float_as_uint(ps), __float_as_uint(ps), false, false);
;       ps = __uint_as_float(rr[0]) + __uint_as_float(rr[1]); }
;     l_reg = l_reg * alpha + ps;
;     ...
;     PK4(p0, 0, pa0); PK4(p0, 8, pa1); PK4(p1, 0, pa2); PK4(p1, 8, pa3);
;     ...
; }
; DI void qkt(f32x16& p0, f32x16& p1, const char* Ks, const bf16x8* qr, const f32x16& negm, int r32, int hi) {
;     { const bf16x8 b0 = *reinterpret_cast<const bf16x8*>(Ks + KSWZ(r32, hi * 16));
;       const bf16x8 b1 = *reinterpret_cast<const bf16x8*>(Ks + KSWZ(32 + r32, hi * 16));
;       p0 = __builtin_amdgcn_mfma_f32_32x32x16_bf16(b0, qr[0], negm, 0, 0, 0);
;       p1 = __builtin_amdgcn_mfma_f32_32x32x16_bf16(b1, qr[0], negm, 0, 0, 0); }
; #pragma unroll
;     for (int d0 = 1; d0 < 4; ++d0) { const int cb = (d0 * 16 + hi * 8) * 2;
;         const bf16x8 b0 = *reinterpret_cast<const bf16x8*>(Ks + KSWZ(r32, cb));
;         const bf16x8 b1 = *reinterpret_cast<const bf16x8*>(Ks + KSWZ(32 + r32, cb));
;         p0 = __builtin_amdgcn_mfma_f32_32x32x16_bf16(b0, qr[d0], p0, 0, 0, 0);
;         p1 = __builtin_amdgcn_mfma_f32_32x32x16_bf16(b1, qr[d0], p1, 0, 0, 0); }
; }
; DI void attn_pass(const bf16_t* __restrict__ Qb, const bf16_t* __restrict__ Kh, const bf16_t* __restrict__ Vh, int seq, char* lds, f32x16 (&o)[4], float& l_out) {
;     ...
;         SBAR(); qkt(pA0, pA1, K_lds, qr, negm, r32, hi);
;         finishSM(pB0, pB1, alB, l_reg, pa0, pa1, pa2, pa3); SBAR();
;         if (j + 3 < NT) SLOADA((j + 3) * KVBLK); SBAR();
.LBB0_1044:
	v_exp_f32_e32 v246, v128
	v_exp_f32_e32 v248, v129
	v_exp_f32_e32 v244, v130
	v_exp_f32_e32 v247, v131
	v_exp_f32_e32 v236, v132
	v_exp_f32_e32 v245, v133
	v_exp_f32_e32 v235, v134
	v_exp_f32_e32 v237, v135
	v_exp_f32_e32 v232, v136
	v_exp_f32_e32 v234, v137
	v_exp_f32_e32 v230, v138
	v_exp_f32_e32 v233, v139
	v_exp_f32_e32 v228, v140
	v_exp_f32_e32 v231, v141
	v_exp_f32_e32 v227, v142
	v_exp_f32_e32 v229, v143
	s_waitcnt lgkmcnt(0)
	s_barrier
	ds_read_b128 v[96:99], v217 offset:32768
	ds_read_b128 v[250:253], v217 offset:36864
	v_exp_f32_e32 v249, v120
	v_exp_f32_e32 v254, v121
	v_exp_f32_e32 v186, v122
	s_waitcnt lgkmcnt(1)
	v_mfma_f32_32x32x16_bf16 v[128:143], v[96:99], v[148:151], v[64:79]
	v_exp_f32_e32 v187, v123
	v_exp_f32_e32 v188, v124
	v_exp_f32_e32 v189, v125
	v_exp_f32_e32 v194, v126
	v_exp_f32_e32 v127, v127
	s_waitcnt lgkmcnt(0)
	v_mfma_f32_32x32x16_bf16 v[96:111], v[250:253], v[148:151], v[64:79]
	ds_read_b128 v[250:253], v218 offset:32768
	ds_read_b128 v[238:241], v218 offset:36864
	s_waitcnt lgkmcnt(1)
	v_mfma_f32_32x32x16_bf16 v[128:143], v[250:253], v[144:147], v[128:143]
	s_waitcnt lgkmcnt(0)
	v_mfma_f32_32x32x16_bf16 v[96:111], v[238:241], v[144:147], v[96:111]
	ds_read_b128 v[238:241], v219 offset:32768
	ds_read_b128 v[250:253], v219 offset:36864
	s_waitcnt lgkmcnt(1)
	v_mfma_f32_32x32x16_bf16 v[128:143], v[238:241], v[152:155], v[128:143]
	s_waitcnt lgkmcnt(0)
	v_mfma_f32_32x32x16_bf16 v[96:111], v[250:253], v[152:155], v[96:111]
	ds_read_b128 v[238:241], v216 offset:32768
	ds_read_b128 v[250:253], v216 offset:36864
	s_waitcnt lgkmcnt(1)
	v_mfma_f32_32x32x16_bf16 v[128:143], v[238:241], v[156:159], v[128:143]
	v_exp_f32_e32 v238, v112
	v_add_f32_e32 v112, v248, v246
	v_add_f32_e32 v112, v244, v112
	v_add_f32_e32 v112, v247, v112
	v_add_f32_e32 v112, v236, v112
	v_add_f32_e32 v112, v245, v112
	v_add_f32_e32 v112, v235, v112
	v_add_f32_e32 v112, v237, v112
	v_add_f32_e32 v112, v232, v112
	v_add_f32_e32 v112, v234, v112
	v_add_f32_e32 v112, v230, v112
	v_add_f32_e32 v112, v233, v112
	v_add_f32_e32 v112, v228, v112
	v_exp_f32_e32 v239, v113
	v_add_f32_e32 v112, v231, v112
	v_exp_f32_e32 v240, v114
	v_add_f32_e32 v112, v227, v112
	v_exp_f32_e32 v241, v115
	v_add_f32_e32 v112, v229, v112
	s_waitcnt lgkmcnt(0)
	v_mfma_f32_32x32x16_bf16 v[96:111], v[250:253], v[156:159], v[96:111]
	v_exp_f32_e32 v250, v116
	v_add_f32_e32 v112, v238, v112
	v_exp_f32_e32 v251, v117
	v_add_f32_e32 v112, v239, v112
	v_exp_f32_e32 v252, v118
	v_add_f32_e32 v112, v240, v112
	v_exp_f32_e32 v253, v119
	v_add_f32_e32 v112, v241, v112
	v_add_f32_e32 v112, v250, v112
	v_add_f32_e32 v112, v251, v112
	v_add_f32_e32 v112, v252, v112
	v_add_f32_e32 v112, v253, v112
	v_add_f32_e32 v112, v249, v112
	v_add_f32_e32 v112, v254, v112
	v_add_f32_e32 v112, v186, v112
	v_add_f32_e32 v112, v187, v112
	v_add_f32_e32 v112, v188, v112
	v_add_f32_e32 v112, v189, v112
	v_add_f32_e32 v112, v194, v112
	v_add_f32_e32 v225, v127, v112
	v_mov_b32_e32 v226, v225
	v_cvt_pk_bf16_f32 v112, v246, v248
	v_cvt_pk_bf16_f32 v113, v244, v247
	v_cvt_pk_bf16_f32 v114, v236, v245
	v_cvt_pk_bf16_f32 v115, v235, v237
	v_cvt_pk_bf16_f32 v116, v232, v234
	v_cvt_pk_bf16_f32 v117, v230, v233
	v_cvt_pk_bf16_f32 v118, v228, v231
	v_cvt_pk_bf16_f32 v119, v227, v229
	v_cvt_pk_bf16_f32 v120, v238, v239
	v_cvt_pk_bf16_f32 v121, v240, v241
	v_cvt_pk_bf16_f32 v122, v250, v251
	v_cvt_pk_bf16_f32 v123, v252, v253
	v_cvt_pk_bf16_f32 v124, v249, v254
	v_cvt_pk_bf16_f32 v125, v186, v187
	v_cvt_pk_bf16_f32 v126, v188, v189
	v_cvt_pk_bf16_f32 v127, v194, v127
	s_nop 1
	v_permlane32_swap_b32_e32 v225, v226
	s_cmp_ge_u32 s2, s22
	s_cselect_b64 s[4:5], -1, 0
	s_and_b64 vcc, exec, s[4:5]
	s_cbranch_vccnz .LBB0_1046
	global_load_dwordx4 v[160:163], v203, s[98:99]
	global_load_dwordx4 v[164:167], v204, s[98:99]
	global_load_dwordx4 v[168:171], v202, s[100:101]
; #define SBAR() __builtin_amdgcn_sched_barrier(0)
; template <int OFF> DI s16x4 tr_read(int vb) { s16x4 r; asm volatile("ds_read_b64_tr_b16 %0, %1 offset:%2" : "=&v"(r) : "v"(vb), "i"(OFF) : "memory"); return r; }
; DI void partialSM(f32x16& p0, f32x16& p1, float& m_reg, f32x16& negm, float& alpha) {
;     constexpr float THR2 = THR * 1.4426950408889634f;
;     float pmax = p0[0];
; #pragma unroll
;     for (int r = 1; r < 16; ++r) pmax = fmaxf(pmax, p0[r]);
; #pragma unroll
;     for (int r = 0; r < 16; ++r) pmax = fmaxf(pmax, p1[r]);
;     { auto rr = __builtin_amdgcn_permlane32_swap(__float_as_uint(pmax), __float_as_uint(pmax), false, false);
;       pmax = fmaxf(__uint_as_float(rr[0]), __uint_as_float(rr[1])); }
;     const bool first = m_reg < -1e29f;
;     if (__builtin_expect(__all(!first && pmax <= THR2), 1)) { alpha = 1.f; }
; template <int D0> DI void pv_one(f32x16& od, int vb, bf16x8 pa0, bf16x8 pa1, bf16x8 pa2, bf16x8 pa3) {
;     const s16x4 l0 = tr_read<v_rd_off(D0, 0, 0)>(vb), h0 = tr_read<v_rd_off(D0, 0, 1)>(vb), l1 = tr_read<v_rd_off(D0, 1, 0)>(vb), h1 = tr_read<v_rd_off(D0, 1, 1)>(vb);
;     const s16x4 l2 = tr_read<v_rd_off(D0, 2, 0)>(vb), h2 = tr_read<v_rd_off(D0, 2, 1)>(vb), l3 = tr_read<v_rd_off(D0, 3, 0)>(vb), h3 = tr_read<v_rd_off(D0, 3, 1)>(vb);
;     asm volatile("s_waitcnt lgkmcnt(0)" ::: "memory"); SBAR();
;     ...
;     od = __builtin_amdgcn_mfma_f32_32x32x16_bf16(pa0, PKV(l0, h0), od, 0, 0, 0);
;     od = __builtin_amdgcn_mfma_f32_32x32x16_bf16(pa1, PKV(l1, h1), od, 0, 0, 0);
;     od = __builtin_amdgcn_mfma_f32_32x32x16_bf16(pa2, PKV(l2, h2), od, 0, 0, 0);
;     od = __builtin_amdgcn_mfma_f32_32x32x16_bf16(pa3, PKV(l3, h3), od, 0, 0, 0);
;     ...
; }
; DI void pv_d0(f32x16* o, int vb, bf16x8 pa0, bf16x8 pa1, bf16x8 pa2, bf16x8 pa3) {
;     pv_one<0>(o[0], vb, pa0, pa1, pa2, pa3); pv_one<1>(o[1], vb, pa0, pa1, pa2, pa3); pv_one<2>(o[2], vb, pa0, pa1, pa2, pa3); pv_one<3>(o[3], vb, pa0, pa1, pa2, pa3);
.LBB0_1046:
	s_add_u32 s98, s98, 0x20000
	s_addc_u32 s99, s99, 0
	s_add_u32 s100, s100, 0x20000
	s_addc_u32 s101, s101, 0
	ds_read_b64_tr_b16 v[206:207], v201 offset:0
	ds_read_b64_tr_b16 v[208:209], v201 offset:0x100
	ds_read_b64_tr_b16 v[228:229], v201 offset:0x1000
	ds_read_b64_tr_b16 v[230:231], v201 offset:0x1100
	ds_read_b64_tr_b16 v[232:233], v201 offset:0x2000
	ds_read_b64_tr_b16 v[234:235], v201 offset:0x2100
	ds_read_b64_tr_b16 v[236:237], v201 offset:0x3000
	ds_read_b64_tr_b16 v[238:239], v201 offset:0x3100
	s_waitcnt lgkmcnt(0)
	s_nop 0
	v_mfma_f32_32x32x16_bf16 v[48:63], v[112:115], v[206:209], v[48:63]
	ds_read_b64_tr_b16 v[206:207], v201 offset:0x200
	ds_read_b64_tr_b16 v[208:209], v201 offset:0x300
	v_mfma_f32_32x32x16_bf16 v[48:63], v[116:119], v[228:231], v[48:63]
	ds_read_b64_tr_b16 v[228:229], v201 offset:0x1200
	ds_read_b64_tr_b16 v[230:231], v201 offset:0x1300
	v_mfma_f32_32x32x16_bf16 v[48:63], v[120:123], v[232:235], v[48:63]
	ds_read_b64_tr_b16 v[232:233], v201 offset:0x2200
	ds_read_b64_tr_b16 v[234:235], v201 offset:0x2300
	v_mfma_f32_32x32x16_bf16 v[48:63], v[124:127], v[236:239], v[48:63]
	ds_read_b64_tr_b16 v[236:237], v201 offset:0x3200
	ds_read_b64_tr_b16 v[238:239], v201 offset:0x3300
	s_waitcnt lgkmcnt(0)
	v_mfma_f32_32x32x16_bf16 v[32:47], v[112:115], v[206:209], v[32:47]
	ds_read_b64_tr_b16 v[206:207], v201 offset:0x400
	ds_read_b64_tr_b16 v[208:209], v201 offset:0x500
	v_mfma_f32_32x32x16_bf16 v[32:47], v[116:119], v[228:231], v[32:47]
	ds_read_b64_tr_b16 v[228:229], v201 offset:0x1400
	ds_read_b64_tr_b16 v[230:231], v201 offset:0x1500
	v_mfma_f32_32x32x16_bf16 v[32:47], v[120:123], v[232:235], v[32:47]
	ds_read_b64_tr_b16 v[232:233], v201 offset:0x2400
	ds_read_b64_tr_b16 v[234:235], v201 offset:0x2500
	v_mfma_f32_32x32x16_bf16 v[32:47], v[124:127], v[236:239], v[32:47]
	ds_read_b64_tr_b16 v[236:237], v201 offset:0x3400
	ds_read_b64_tr_b16 v[238:239], v201 offset:0x3500
	s_waitcnt lgkmcnt(0)
	v_mfma_f32_32x32x16_bf16 v[16:31], v[112:115], v[206:209], v[16:31]
	ds_read_b64_tr_b16 v[206:207], v201 offset:0x600
	ds_read_b64_tr_b16 v[208:209], v201 offset:0x700
	v_mfma_f32_32x32x16_bf16 v[16:31], v[116:119], v[228:231], v[16:31]
	ds_read_b64_tr_b16 v[228:229], v201 offset:0x1600
	ds_read_b64_tr_b16 v[230:231], v201 offset:0x1700
	v_mfma_f32_32x32x16_bf16 v[16:31], v[120:123], v[232:235], v[16:31]
	ds_read_b64_tr_b16 v[232:233], v201 offset:0x2600
	ds_read_b64_tr_b16 v[234:235], v201 offset:0x2700
	v_mfma_f32_32x32x16_bf16 v[16:31], v[124:127], v[236:239], v[16:31]
	ds_read_b64_tr_b16 v[236:237], v201 offset:0x3600
	ds_read_b64_tr_b16 v[238:239], v201 offset:0x3700
	s_waitcnt lgkmcnt(0)
	v_mfma_f32_32x32x16_bf16 v[0:15], v[112:115], v[206:209], v[0:15]
	v_max_f32_e32 v112, v128, v129
	v_max3_f32 v112, v112, v130, v131
	v_max3_f32 v112, v112, v132, v133
	v_max3_f32 v112, v112, v134, v135
	v_max3_f32 v112, v112, v136, v137
	v_mfma_f32_32x32x16_bf16 v[0:15], v[116:119], v[228:231], v[0:15]
	v_max3_f32 v112, v112, v138, v139
	v_max3_f32 v112, v112, v140, v141
	v_max3_f32 v112, v112, v142, v143
	v_max3_f32 v112, v112, v96, v97
	v_max3_f32 v112, v112, v98, v99
	v_max3_f32 v112, v112, v100, v101
	v_max3_f32 v112, v112, v102, v103
	v_mfma_f32_32x32x16_bf16 v[0:15], v[120:123], v[232:235], v[0:15]
	v_max3_f32 v112, v112, v104, v105
	v_max3_f32 v112, v112, v106, v107
	v_max3_f32 v112, v112, v108, v109
	v_max3_f32 v112, v112, v110, v111
	v_mov_b32_e32 v113, v112
	s_nop 1
	v_permlane32_swap_b32_e32 v112, v113
	v_mfma_f32_32x32x16_bf16 v[0:15], v[124:127], v[236:239], v[0:15]
	v_max_f32_e32 v113, v112, v113
	v_cmp_ngt_f32_e32 vcc, s83, v200
	v_cmp_ge_f32_e64 s[8:9], s63, v113
	s_and_b64 s[8:9], vcc, s[8:9]
	s_cmp_eq_u64 s[8:9], exec
	v_mov_b32_e32 v112, 1.0
	s_cbranch_scc0 .LBB0_1058

; DI void finishSM(f32x16& p0, f32x16& p1, float alpha, float& l_reg, bf16x8& pa0, bf16x8& pa1, bf16x8& pa2, bf16x8& pa3) {
; #pragma unroll
;     for (int r = 0; r < 16; ++r) p1[r] = __builtin_amdgcn_exp2f(p1[r]);
;     float ps = 0;
; #pragma unroll
;     for (int r = 0; r < 16; ++r) ps += p0[r];
; #pragma unroll
;     for (int r = 0; r < 16; ++r) ps += p1[r];
;     { auto rr = __builtin_amdgcn_permlane32_swap(__float_as_uint(ps), __float_as_uint(ps), false, false);
;       ps = __uint_as_float(rr[0]) + __uint_as_float(rr[1]); }
;     l_reg = l_reg * alpha + ps;
;     ...
;     PK4(p0, 0, pa0); PK4(p0, 8, pa1); PK4(p1, 0, pa2); PK4(p1, 8, pa3);
;     ...
; }
; DI void qkt(f32x16& p0, f32x16& p1, const char* Ks, const bf16x8* qr, const f32x16& negm, int r32, int hi) {
;     { const bf16x8 b0 = *reinterpret_cast<const bf16x8*>(Ks + KSWZ(r32, hi * 16));
;       const bf16x8 b1 = *reinterpret_cast<const bf16x8*>(Ks + KSWZ(32 + r32, hi * 16));
;       p0 = __builtin_amdgcn_mfma_f32_32x32x16_bf16(b0, qr[0], negm, 0, 0, 0);
;       p1 = __builtin_amdgcn_mfma_f32_32x32x16_bf16(b1, qr[0], negm, 0, 0, 0); }
; #pragma unroll
;     for (int d0 = 1; d0 < 4; ++d0) { const int cb = (d0 * 16 + hi * 8) * 2;
;         const bf16x8 b0 = *reinterpret_cast<const bf16x8*>(Ks + KSWZ(r32, cb));
;         const bf16x8 b1 = *reinterpret_cast<const bf16x8*>(Ks + KSWZ(32 + r32, cb));
;         p0 = __builtin_amdgcn_mfma_f32_32x32x16_bf16(b0, qr[d0], p0, 0, 0, 0);
;         p1 = __builtin_amdgcn_mfma_f32_32x32x16_bf16(b1, qr[d0], p1, 0, 0, 0); }
; }
; DI int v_st(int k, int c) { const int kk = (k & ~0xC) | ((k & 4) << 1) | ((k & 8) >> 1); return ((kk >> 3) * 4 + (c >> 5)) * 512 + ((kk & 7) * 32 + (c & 31)) * 2; }
; DI int v_rd_base(int lane) { return ((lane & 3) << 3) | (((lane >> 2) & 3) << 6) | (((lane >> 4) & 1) << 5) | (((lane >> 5) & 1) << 8); }
; template <int OFF> DI s16x4 tr_read(int vb) { s16x4 r; asm volatile("ds_read_b64_tr_b16 %0, %1 offset:%2" : "=&v"(r) : "v"(vb), "i"(OFF) : "memory"); return r; }
; template <int D0> DI void pv_one(f32x16& od, int vb, bf16x8 pa0, bf16x8 pa1, bf16x8 pa2, bf16x8 pa3) {
;     const s16x4 l0 = tr_read<v_rd_off(D0, 0, 0)>(vb), h0 = tr_read<v_rd_off(D0, 0, 1)>(vb), l1 = tr_read<v_rd_off(D0, 1, 0)>(vb), h1 = tr_read<v_rd_off(D0, 1, 1)>(vb);
.LBB0_1059:
	v_mov_b64_e32 v[94:95], v[78:79]
	v_mov_b64_e32 v[92:93], v[76:77]
	v_mov_b64_e32 v[90:91], v[74:75]
	v_mov_b64_e32 v[88:89], v[72:73]
	v_mov_b64_e32 v[86:87], v[70:71]
	v_mov_b64_e32 v[84:85], v[68:69]
	v_mov_b64_e32 v[82:83], v[66:67]
	v_mov_b64_e32 v[80:81], v[64:65]
	ds_read_b128 v[114:117], v217 offset:40960
	ds_read_b128 v[118:121], v217 offset:45056
	v_exp_f32_e32 v113, v97
	v_add_f32_e32 v97, 0, v207
	v_add_f32_e32 v97, v209, v97
	s_waitcnt lgkmcnt(1)
	v_mfma_f32_32x32x16_bf16 v[64:79], v[114:117], v[148:151], v[80:95]
	v_add_f32_e32 v97, v183, v97
	v_add_f32_e32 v97, v208, v97
	v_add_f32_e32 v97, v181, v97
	v_add_f32_e32 v97, v206, v97
	v_add_f32_e32 v97, v180, v97
	v_add_f32_e32 v97, v182, v97
	v_add_f32_e32 v97, v173, v97
	s_waitcnt lgkmcnt(0)
	v_mfma_f32_32x32x16_bf16 v[80:95], v[118:121], v[148:151], v[80:95]
	ds_read_b128 v[114:117], v218 offset:40960
	ds_read_b128 v[118:121], v218 offset:45056
	v_add_f32_e32 v97, v175, v97
	v_add_f32_e32 v97, v172, v97
	v_add_f32_e32 v97, v174, v97
	v_exp_f32_e32 v96, v96
	v_add_f32_e32 v97, v177, v97
	v_add_f32_e32 v97, v179, v97
	s_waitcnt lgkmcnt(1)
	v_mfma_f32_32x32x16_bf16 v[64:79], v[114:117], v[144:147], v[64:79]
	v_add_f32_e32 v97, v176, v97
	v_exp_f32_e32 v99, v99
	v_add_f32_e32 v97, v178, v97
	v_add_f32_e32 v97, v96, v97
	v_add_f32_e32 v97, v113, v97
	v_exp_f32_e32 v122, v107
	v_exp_f32_e32 v123, v108
	s_waitcnt lgkmcnt(0)
	v_mfma_f32_32x32x16_bf16 v[80:95], v[118:121], v[144:147], v[80:95]
	ds_read_b128 v[114:117], v219 offset:40960
	ds_read_b128 v[118:121], v219 offset:45056
	v_exp_f32_e32 v124, v109
	v_exp_f32_e32 v125, v110
	v_exp_f32_e32 v126, v111
	s_waitcnt lgkmcnt(1)
	v_mfma_f32_32x32x16_bf16 v[64:79], v[114:117], v[152:155], v[64:79]
	s_waitcnt lgkmcnt(0)
	v_mfma_f32_32x32x16_bf16 v[80:95], v[118:121], v[152:155], v[80:95]
	ds_read_b128 v[114:117], v216 offset:40960
	ds_read_b128 v[118:121], v216 offset:45056
	s_waitcnt lgkmcnt(1)
	v_mfma_f32_32x32x16_bf16 v[64:79], v[114:117], v[156:159], v[64:79]
	v_exp_f32_e32 v114, v98
	v_exp_f32_e32 v115, v100
	v_exp_f32_e32 v116, v101
	v_exp_f32_e32 v117, v102
	v_add_f32_e32 v97, v114, v97
	v_add_f32_e32 v97, v99, v97
	v_add_f32_e32 v97, v115, v97
	s_waitcnt lgkmcnt(0)
	v_mfma_f32_32x32x16_bf16 v[80:95], v[118:121], v[156:159], v[80:95]
	v_exp_f32_e32 v118, v103
	v_exp_f32_e32 v119, v104
	v_exp_f32_e32 v120, v105
	v_add_f32_e32 v97, v116, v97
	v_exp_f32_e32 v121, v106
	v_add_f32_e32 v97, v117, v97
	v_add_f32_e32 v97, v118, v97
	v_add_f32_e32 v97, v119, v97
	v_add_f32_e32 v97, v120, v97
	v_add_f32_e32 v97, v121, v97
	v_add_f32_e32 v97, v122, v97
	v_add_f32_e32 v97, v123, v97
	v_add_f32_e32 v97, v124, v97
	v_add_f32_e32 v97, v125, v97
	v_add_f32_e32 v97, v126, v97
	v_mov_b32_e32 v98, v97
	s_nop 1
	v_permlane32_swap_b32_e32 v97, v98
	v_cvt_pk_bf16_f32 v100, v207, v209
	v_cvt_pk_bf16_f32 v101, v183, v208
	v_cvt_pk_bf16_f32 v102, v181, v206
	v_cvt_pk_bf16_f32 v103, v180, v182
	v_cvt_pk_bf16_f32 v104, v173, v175
	v_cvt_pk_bf16_f32 v105, v172, v174
	v_cvt_pk_bf16_f32 v106, v177, v179
	v_cvt_pk_bf16_f32 v107, v176, v178
	v_cvt_pk_bf16_f32 v108, v96, v113
	v_cvt_pk_bf16_f32 v109, v114, v99
	v_cvt_pk_bf16_f32 v110, v115, v116
	v_cvt_pk_bf16_f32 v111, v117, v118
	v_cvt_pk_bf16_f32 v114, v119, v120
	v_cvt_pk_bf16_f32 v115, v121, v122
	v_cvt_pk_bf16_f32 v116, v123, v124
	v_cvt_pk_bf16_f32 v117, v125, v126
	s_nop 0
	ds_read_b64_tr_b16 v[118:119], v220 offset:0
	ds_read_b64_tr_b16 v[120:121], v220 offset:0x100
	ds_read_b64_tr_b16 v[122:123], v220 offset:0x1000
	ds_read_b64_tr_b16 v[124:125], v220 offset:0x1100
	ds_read_b64_tr_b16 v[126:127], v220 offset:0x2000
	ds_read_b64_tr_b16 v[128:129], v220 offset:0x2100
	ds_read_b64_tr_b16 v[130:131], v220 offset:0x3000
	ds_read_b64_tr_b16 v[132:133], v220 offset:0x3100
	s_waitcnt lgkmcnt(0)
; #define SBAR() __builtin_amdgcn_sched_barrier(0)
; template <int OFF> DI s16x4 tr_read(int vb) { s16x4 r; asm volatile("ds_read_b64_tr_b16 %0, %1 offset:%2" : "=&v"(r) : "v"(vb), "i"(OFF) : "memory"); return r; }
; DI void partialSM(f32x16& p0, f32x16& p1, float& m_reg, f32x16& negm, float& alpha) {
;     constexpr float THR2 = THR * 1.4426950408889634f;
;     float pmax = p0[0];
; #pragma unroll
;     for (int r = 1; r < 16; ++r) pmax = fmaxf(pmax, p0[r]);
; #pragma unroll
;     for (int r = 0; r < 16; ++r) pmax = fmaxf(pmax, p1[r]);
;     { auto rr = __builtin_amdgcn_permlane32_swap(__float_as_uint(pmax), __float_as_uint(pmax), false, false);
;       pmax = fmaxf(__uint_as_float(rr[0]), __uint_as_float(rr[1])); }
;     const bool first = m_reg < -1e29f;
;     if (__builtin_expect(__all(!first && pmax <= THR2), 1)) { alpha = 1.f; }
; template <int D0> DI void pv_one(f32x16& od, int vb, bf16x8 pa0, bf16x8 pa1, bf16x8 pa2, bf16x8 pa3) {
;     const s16x4 l0 = tr_read<v_rd_off(D0, 0, 0)>(vb), h0 = tr_read<v_rd_off(D0, 0, 1)>(vb), l1 = tr_read<v_rd_off(D0, 1, 0)>(vb), h1 = tr_read<v_rd_off(D0, 1, 1)>(vb);
;     const s16x4 l2 = tr_read<v_rd_off(D0, 2, 0)>(vb), h2 = tr_read<v_rd_off(D0, 2, 1)>(vb), l3 = tr_read<v_rd_off(D0, 3, 0)>(vb), h3 = tr_read<v_rd_off(D0, 3, 1)>(vb);
;     asm volatile("s_waitcnt lgkmcnt(0)" ::: "memory"); SBAR();
;     ...
;     od = __builtin_amdgcn_mfma_f32_32x32x16_bf16(pa0, PKV(l0, h0), od, 0, 0, 0);
;     od = __builtin_amdgcn_mfma_f32_32x32x16_bf16(pa1, PKV(l1, h1), od, 0, 0, 0);
;     od = __builtin_amdgcn_mfma_f32_32x32x16_bf16(pa2, PKV(l2, h2), od, 0, 0, 0);
;     od = __builtin_amdgcn_mfma_f32_32x32x16_bf16(pa3, PKV(l3, h3), od, 0, 0, 0);
;     ...
; }
; DI void pv_d0(f32x16* o, int vb, bf16x8 pa0, bf16x8 pa1, bf16x8 pa2, bf16x8 pa3) {
;     pv_one<0>(o[0], vb, pa0, pa1, pa2, pa3); pv_one<1>(o[1], vb, pa0, pa1, pa2, pa3); pv_one<2>(o[2], vb, pa0, pa1, pa2, pa3); pv_one<3>(o[3], vb, pa0, pa1, pa2, pa3);
	s_nop 0
	v_mfma_f32_32x32x16_bf16 v[48:63], v[100:103], v[118:121], v[48:63]
	ds_read_b64_tr_b16 v[118:119], v220 offset:0x200
	ds_read_b64_tr_b16 v[120:121], v220 offset:0x300
	v_mfma_f32_32x32x16_bf16 v[48:63], v[104:107], v[122:125], v[48:63]
	ds_read_b64_tr_b16 v[122:123], v220 offset:0x1200
	ds_read_b64_tr_b16 v[124:125], v220 offset:0x1300
	v_mfma_f32_32x32x16_bf16 v[48:63], v[108:111], v[126:129], v[48:63]
	ds_read_b64_tr_b16 v[126:127], v220 offset:0x2200
	ds_read_b64_tr_b16 v[128:129], v220 offset:0x2300
	v_mfma_f32_32x32x16_bf16 v[48:63], v[114:117], v[130:133], v[48:63]
	ds_read_b64_tr_b16 v[130:131], v220 offset:0x3200
	ds_read_b64_tr_b16 v[132:133], v220 offset:0x3300
	s_waitcnt lgkmcnt(0)
	v_mfma_f32_32x32x16_bf16 v[32:47], v[100:103], v[118:121], v[32:47]
	ds_read_b64_tr_b16 v[118:119], v220 offset:0x400
	ds_read_b64_tr_b16 v[120:121], v220 offset:0x500
	v_mfma_f32_32x32x16_bf16 v[32:47], v[104:107], v[122:125], v[32:47]
	ds_read_b64_tr_b16 v[122:123], v220 offset:0x1400
	ds_read_b64_tr_b16 v[124:125], v220 offset:0x1500
	v_mfma_f32_32x32x16_bf16 v[32:47], v[108:111], v[126:129], v[32:47]
	ds_read_b64_tr_b16 v[126:127], v220 offset:0x2400
	ds_read_b64_tr_b16 v[128:129], v220 offset:0x2500
	v_mfma_f32_32x32x16_bf16 v[32:47], v[114:117], v[130:133], v[32:47]
	ds_read_b64_tr_b16 v[130:131], v220 offset:0x3400
	ds_read_b64_tr_b16 v[132:133], v220 offset:0x3500
	s_waitcnt lgkmcnt(0)
	v_mfma_f32_32x32x16_bf16 v[16:31], v[100:103], v[118:121], v[16:31]
	ds_read_b64_tr_b16 v[118:119], v220 offset:0x600
	ds_read_b64_tr_b16 v[120:121], v220 offset:0x700
	v_mfma_f32_32x32x16_bf16 v[16:31], v[104:107], v[122:125], v[16:31]
	ds_read_b64_tr_b16 v[122:123], v220 offset:0x1600
	ds_read_b64_tr_b16 v[124:125], v220 offset:0x1700
	v_mfma_f32_32x32x16_bf16 v[16:31], v[108:111], v[126:129], v[16:31]
	ds_read_b64_tr_b16 v[126:127], v220 offset:0x2600
	ds_read_b64_tr_b16 v[128:129], v220 offset:0x2700
	v_mfma_f32_32x32x16_bf16 v[16:31], v[114:117], v[130:133], v[16:31]
	ds_read_b64_tr_b16 v[130:131], v220 offset:0x3600
	ds_read_b64_tr_b16 v[132:133], v220 offset:0x3700
	s_waitcnt lgkmcnt(0)
	v_mfma_f32_32x32x16_bf16 v[0:15], v[100:103], v[118:121], v[0:15]
	v_max_f32_e32 v96, v65, v65
	v_max_f32_e32 v99, v64, v64
	v_max_f32_e32 v96, v99, v96
	v_max3_f32 v96, v96, v66, v67
	v_max3_f32 v96, v96, v68, v69
	v_max3_f32 v96, v96, v70, v71
	v_max3_f32 v96, v96, v72, v73
	v_mfma_f32_32x32x16_bf16 v[0:15], v[104:107], v[122:125], v[0:15]
	v_max3_f32 v96, v96, v74, v75
	v_max3_f32 v96, v96, v76, v77
	v_max3_f32 v96, v96, v78, v79
	v_max3_f32 v96, v96, v80, v81
	v_max3_f32 v96, v96, v82, v83
	v_max3_f32 v96, v96, v84, v85
	v_max3_f32 v96, v96, v86, v87
	v_mfma_f32_32x32x16_bf16 v[0:15], v[108:111], v[126:129], v[0:15]
	v_max3_f32 v96, v96, v88, v89
	v_max3_f32 v96, v96, v90, v91
	v_max3_f32 v96, v96, v92, v93
	v_max3_f32 v96, v96, v94, v95
	v_mov_b32_e32 v99, v96
	s_nop 1
	v_permlane32_swap_b32_e32 v96, v99
	v_mfma_f32_32x32x16_bf16 v[0:15], v[114:117], v[130:133], v[0:15]
	v_max_f32_e32 v99, v99, v99
	v_max_f32_e32 v96, v96, v96
	v_max_f32_e32 v96, v96, v99
	v_cmp_ngt_f32_e32 vcc, s83, v200
	v_cmp_ge_f32_e64 s[8:9], s63, v96
	s_and_b64 s[4:5], vcc, s[8:9]
	v_cndmask_b32_e64 v99, 0, 1, s[4:5]
	v_cmp_ne_u32_e64 s[8:9], 0, v99
	v_mov_b32_e32 v99, 1.0
	s_cmp_eq_u64 s[8:9], exec
	s_cbranch_scc0 .LBB0_1071

; DI void finishSM(f32x16& p0, f32x16& p1, float alpha, float& l_reg, bf16x8& pa0, bf16x8& pa1, bf16x8& pa2, bf16x8& pa3) {
; #pragma unroll
;     for (int r = 0; r < 16; ++r) p1[r] = __builtin_amdgcn_exp2f(p1[r]);
;     float ps = 0;
; #pragma unroll
;     for (int r = 0; r < 16; ++r) ps += p0[r];
; #pragma unroll
;     for (int r = 0; r < 16; ++r) ps += p1[r];
;     { auto rr = __builtin_amdgcn_permlane32_swap(__float_as_uint(ps), __float_as_uint(ps), false, false);
;       ps = __uint_as_float(rr[0]) + __uint_as_float(rr[1]); }
;     l_reg = l_reg * alpha + ps;
;     ...
;     PK4(p0, 0, pa0); PK4(p0, 8, pa1); PK4(p1, 0, pa2); PK4(p1, 8, pa3);
;     ...
; }
; DI void qkt(f32x16& p0, f32x16& p1, const char* Ks, const bf16x8* qr, const f32x16& negm, int r32, int hi) {
;     { const bf16x8 b0 = *reinterpret_cast<const bf16x8*>(Ks + KSWZ(r32, hi * 16));
;       const bf16x8 b1 = *reinterpret_cast<const bf16x8*>(Ks + KSWZ(32 + r32, hi * 16));
;       p0 = __builtin_amdgcn_mfma_f32_32x32x16_bf16(b0, qr[0], negm, 0, 0, 0);
;       p1 = __builtin_amdgcn_mfma_f32_32x32x16_bf16(b1, qr[0], negm, 0, 0, 0); }
; #pragma unroll
;     for (int d0 = 1; d0 < 4; ++d0) { const int cb = (d0 * 16 + hi * 8) * 2;
;         const bf16x8 b0 = *reinterpret_cast<const bf16x8*>(Ks + KSWZ(r32, cb));
;         const bf16x8 b1 = *reinterpret_cast<const bf16x8*>(Ks + KSWZ(32 + r32, cb));
;         p0 = __builtin_amdgcn_mfma_f32_32x32x16_bf16(b0, qr[d0], p0, 0, 0, 0);
;         p1 = __builtin_amdgcn_mfma_f32_32x32x16_bf16(b1, qr[d0], p1, 0, 0, 0); }
; }
; DI int v_st(int k, int c) { const int kk = (k & ~0xC) | ((k & 4) << 1) | ((k & 8) >> 1); return ((kk >> 3) * 4 + (c >> 5)) * 512 + ((kk & 7) * 32 + (c & 31)) * 2; }
; DI int v_rd_base(int lane) { return ((lane & 3) << 3) | (((lane >> 2) & 3) << 6) | (((lane >> 4) & 1) << 5) | (((lane >> 5) & 1) << 8); }
; template <int OFF> DI s16x4 tr_read(int vb) { s16x4 r; asm volatile("ds_read_b64_tr_b16 %0, %1 offset:%2" : "=&v"(r) : "v"(vb), "i"(OFF) : "memory"); return r; }
; template <int D0> DI void pv_one(f32x16& od, int vb, bf16x8 pa0, bf16x8 pa1, bf16x8 pa2, bf16x8 pa3) {
;     const s16x4 l0 = tr_read<v_rd_off(D0, 0, 0)>(vb), h0 = tr_read<v_rd_off(D0, 0, 1)>(vb), l1 = tr_read<v_rd_off(D0, 1, 0)>(vb), h1 = tr_read<v_rd_off(D0, 1, 1)>(vb);
.LBB0_1064:
	v_exp_f32_e32 v64, v64
	v_exp_f32_e32 v100, v68
	v_exp_f32_e32 v68, v65
	v_exp_f32_e32 v66, v66
	v_exp_f32_e32 v96, v70
	v_exp_f32_e32 v70, v69
	v_exp_f32_e32 v69, v67
	v_add_f32_e32 v65, 0, v64
	v_add_f32_e32 v65, v68, v65
	v_add_f32_e32 v65, v66, v65
	v_exp_f32_e32 v71, v71
	v_add_f32_e32 v65, v69, v65
	v_exp_f32_e32 v72, v72
	v_add_f32_e32 v65, v100, v65
	v_exp_f32_e32 v73, v73
	v_add_f32_e32 v65, v70, v65
	v_exp_f32_e32 v74, v74
	v_add_f32_e32 v65, v96, v65
	v_exp_f32_e32 v75, v75
	v_add_f32_e32 v65, v71, v65
	v_exp_f32_e32 v76, v76
	v_add_f32_e32 v65, v72, v65
	v_exp_f32_e32 v77, v77
	v_add_f32_e32 v65, v73, v65
	v_exp_f32_e32 v78, v78
	v_add_f32_e32 v65, v74, v65
	v_exp_f32_e32 v79, v79
	v_add_f32_e32 v65, v75, v65
	v_exp_f32_e32 v80, v80
	v_add_f32_e32 v65, v76, v65
	v_exp_f32_e32 v81, v81
	v_add_f32_e32 v65, v77, v65
	v_exp_f32_e32 v82, v82
	v_add_f32_e32 v65, v78, v65
	v_exp_f32_e32 v83, v83
	v_add_f32_e32 v65, v79, v65
	v_exp_f32_e32 v84, v84
	v_add_f32_e32 v65, v80, v65
	v_exp_f32_e32 v85, v85
	v_add_f32_e32 v65, v81, v65
	v_exp_f32_e32 v86, v86
	v_add_f32_e32 v65, v82, v65
	v_exp_f32_e32 v87, v87
	v_add_f32_e32 v65, v83, v65
	v_exp_f32_e32 v88, v88
	v_add_f32_e32 v65, v84, v65
	v_exp_f32_e32 v89, v89
	v_add_f32_e32 v65, v85, v65
	v_exp_f32_e32 v90, v90
	v_add_f32_e32 v65, v86, v65
	v_exp_f32_e32 v91, v91
	v_add_f32_e32 v65, v87, v65
	v_exp_f32_e32 v92, v92
	v_add_f32_e32 v65, v88, v65
	v_exp_f32_e32 v93, v93
	v_add_f32_e32 v65, v89, v65
	v_exp_f32_e32 v94, v94
	v_add_f32_e32 v65, v90, v65
	v_exp_f32_e32 v95, v95
	v_add_f32_e32 v65, v91, v65
	v_add_f32_e32 v65, v92, v65
	v_add_f32_e32 v65, v93, v65
	v_add_f32_e32 v65, v94, v65
	v_add_f32_e32 v65, v95, v65
	v_mov_b32_e32 v67, v65
	v_cvt_pk_bf16_f32 v68, v64, v68
	v_cvt_pk_bf16_f32 v69, v66, v69
	v_cvt_pk_bf16_f32 v70, v100, v70
	v_cvt_pk_bf16_f32 v71, v96, v71
	s_nop 1
	v_permlane32_swap_b32_e32 v65, v67
	v_cvt_pk_bf16_f32 v72, v72, v73
	v_cvt_pk_bf16_f32 v73, v74, v75
	v_cvt_pk_bf16_f32 v74, v76, v77
	v_cvt_pk_bf16_f32 v75, v78, v79
	v_cvt_pk_bf16_f32 v76, v80, v81
	v_cvt_pk_bf16_f32 v77, v82, v83
	v_cvt_pk_bf16_f32 v78, v84, v85
	v_cvt_pk_bf16_f32 v79, v86, v87
	v_cvt_pk_bf16_f32 v80, v88, v89
	v_cvt_pk_bf16_f32 v81, v90, v91
	v_cvt_pk_bf16_f32 v82, v92, v93
	v_cvt_pk_bf16_f32 v83, v94, v95
	s_nop 0
	ds_read_b64_tr_b16 v[84:85], v201 offset:0
	ds_read_b64_tr_b16 v[86:87], v201 offset:0x100
	ds_read_b64_tr_b16 v[88:89], v201 offset:0x1000
	ds_read_b64_tr_b16 v[90:91], v201 offset:0x1100
	ds_read_b64_tr_b16 v[92:93], v201 offset:0x2000
	ds_read_b64_tr_b16 v[94:95], v201 offset:0x2100
	ds_read_b64_tr_b16 v[100:101], v201 offset:0x3000
	ds_read_b64_tr_b16 v[102:103], v201 offset:0x3100
	s_waitcnt lgkmcnt(0)
	s_nop 0
	v_mfma_f32_32x32x16_bf16 v[48:63], v[68:71], v[84:87], v[48:63]
	ds_read_b64_tr_b16 v[84:85], v201 offset:0x200
	ds_read_b64_tr_b16 v[86:87], v201 offset:0x300
	v_mfma_f32_32x32x16_bf16 v[48:63], v[72:75], v[88:91], v[48:63]
	ds_read_b64_tr_b16 v[88:89], v201 offset:0x1200
	ds_read_b64_tr_b16 v[90:91], v201 offset:0x1300
	v_mfma_f32_32x32x16_bf16 v[48:63], v[76:79], v[92:95], v[48:63]
	ds_read_b64_tr_b16 v[92:93], v201 offset:0x2200
	ds_read_b64_tr_b16 v[94:95], v201 offset:0x2300
	v_mfma_f32_32x32x16_bf16 v[48:63], v[80:83], v[100:103], v[48:63]
	ds_read_b64_tr_b16 v[100:101], v201 offset:0x3200
	ds_read_b64_tr_b16 v[102:103], v201 offset:0x3300
	s_waitcnt lgkmcnt(0)
	v_mfma_f32_32x32x16_bf16 v[32:47], v[68:71], v[84:87], v[32:47]
	ds_read_b64_tr_b16 v[84:85], v201 offset:0x400
	ds_read_b64_tr_b16 v[86:87], v201 offset:0x500
	v_mfma_f32_32x32x16_bf16 v[32:47], v[72:75], v[88:91], v[32:47]
	ds_read_b64_tr_b16 v[88:89], v201 offset:0x1400
	ds_read_b64_tr_b16 v[90:91], v201 offset:0x1500
	v_mfma_f32_32x32x16_bf16 v[32:47], v[76:79], v[92:95], v[32:47]
	ds_read_b64_tr_b16 v[92:93], v201 offset:0x2400
	ds_read_b64_tr_b16 v[94:95], v201 offset:0x2500
	v_mfma_f32_32x32x16_bf16 v[32:47], v[80:83], v[100:103], v[32:47]
	ds_read_b64_tr_b16 v[100:101], v201 offset:0x3400
	ds_read_b64_tr_b16 v[102:103], v201 offset:0x3500
	s_waitcnt lgkmcnt(0)
	v_mfma_f32_32x32x16_bf16 v[16:31], v[68:71], v[84:87], v[16:31]
	ds_read_b64_tr_b16 v[84:85], v201 offset:0x600
	ds_read_b64_tr_b16 v[86:87], v201 offset:0x700
	v_mfma_f32_32x32x16_bf16 v[16:31], v[72:75], v[88:91], v[16:31]
	ds_read_b64_tr_b16 v[88:89], v201 offset:0x1600
	ds_read_b64_tr_b16 v[90:91], v201 offset:0x1700
	v_mfma_f32_32x32x16_bf16 v[16:31], v[76:79], v[92:95], v[16:31]
	ds_read_b64_tr_b16 v[92:93], v201 offset:0x2600
	ds_read_b64_tr_b16 v[94:95], v201 offset:0x2700
	v_mfma_f32_32x32x16_bf16 v[16:31], v[80:83], v[100:103], v[16:31]
	ds_read_b64_tr_b16 v[100:101], v201 offset:0x3600
	ds_read_b64_tr_b16 v[102:103], v201 offset:0x3700
	s_waitcnt lgkmcnt(0)
	v_mfma_f32_32x32x16_bf16 v[0:15], v[68:71], v[84:87], v[0:15]
	v_mov_b32_e32 v96, v199
	s_mov_b64 s[4:5], s[0:1]
	s_load_dwordx2 s[4:5], s[4:5], 0x110
	v_and_b32_e32 v71, 63, v96
	v_and_b32_e32 v64, 0x3fffffc0, v96
	v_mfma_f32_32x32x16_bf16 v[0:15], v[72:75], v[88:91], v[0:15]
	v_and_b32_e32 v69, 31, v96
	v_lshl_add_u32 v68, v64, 2, 0
	v_cmp_gt_u32_e32 vcc, 32, v71
	v_mfma_f32_32x32x16_bf16 v[0:15], v[76:79], v[92:95], v[0:15]
	v_mfma_f32_32x32x16_bf16 v[0:15], v[80:83], v[100:103], v[0:15]
	s_and_saveexec_b64 s[6:7], vcc
	s_cbranch_execz .LBB0_1066
	v_mul_f32_e32 v64, v210, v112
	v_add_f32_e32 v66, v97, v98
	v_pk_add_f32 v[64:65], v[64:65], v[66:67]
	v_lshl_add_u32 v70, v69, 2, v68
	v_fmac_f32_e32 v65, v64, v99
	ds_write_b32 v70, v65 offset:49152
